# P7 merge epilogue: separate straight-line copy for the last branch unit with the unused next-gate reciprocal chains removed (factor max(g,1e-6) times 1.0 folded)
# baseline (speedup 1.0000x reference)
;     __device__ __forceinline__ void operator()(f32x4 (&acc)[2][2][4][2], const Unit& u, int wr, int wc, int fr, int fq) const {
;         const int row0 = u.pm * BM + wr * 64 + fr, col0 = u.pn * BM + wc * 32 + 8 * fq;
;         const bool last = (u.kind == 2);
;         const int koff = 5120 + u.kind * 2048, noff = last ? 0 : 2048;
; #pragma unroll
;         for (int ai = 0; ai < 2; ++ai)
; #pragma unroll
;             for (int m2 = 0; m2 < 2; ++m2) {
;                 u32x4 ga[2][2], gb[2][2];
; #pragma unroll
;                 for (int mm = 0; mm < 2; ++mm)
; #pragma unroll
;                     for (int bj = 0; bj < 2; ++bj) {
;                         const bf16_t* zp = Z + (size_t)(row0 + ai * HALF + (2 * m2 + mm) * 16) * NZ + koff + col0 + bj * HALF;
;                         ga[mm][bj] = *(const u32x4*)zp;
;                         gb[mm][bj] = *(const u32x4*)(zp + noff);
;                     }
; #pragma unroll
;                 for (int mm = 0; mm < 2; ++mm)
; #pragma unroll
;                     for (int bj = 0; bj < 2; ++bj) {
;                         const int m = 2 * m2 + mm;
;                         const u32x4 a4 = ga[mm][bj], b4 = gb[mm][bj];
;                         f32x4 g0 = (f32x4){bflo(a4.x), bfhi(a4.x), bflo(a4.y), bfhi(a4.y)}, g1 = (f32x4){bflo(a4.z), bfhi(a4.z), bflo(a4.w), bfhi(a4.w)};
;                         const f32x4 h0 = (f32x4){bflo(b4.x), bfhi(b4.x), bflo(b4.y), bfhi(b4.y)}, h1 = (f32x4){bflo(b4.z), bfhi(b4.z), bflo(b4.w), bfhi(b4.w)};
; #pragma unroll
;                         for (int j = 0; j < 4; ++j) {
;                             g0[j] = fmaxf(g0[j], 1e-6f) * (last ? 1.0f : __builtin_amdgcn_rcpf(fmaxf(h0[j], 1e-6f)));
;                             g1[j] = fmaxf(g1[j], 1e-6f) * (last ? 1.0f : __builtin_amdgcn_rcpf(fmaxf(h1[j], 1e-6f)));
;                         }
;                         acc[ai][bj][m][0] *= g0; acc[ai][bj][m][1] *= g1;
;                         if (last) {
;                             const f32x4 v0 = acc[ai][bj][m][0], v1 = acc[ai][bj][m][1];
;                             u32x4 w; w.x = cvt_pk_bf16(v0[0], v0[1]); w.y = cvt_pk_bf16(v0[2], v0[3]); w.z = cvt_pk_bf16(v1[0], v1[1]); w.w = cvt_pk_bf16(v1[2], v1[3]);
;                             *(u32x4*)(MB + (size_t)(row0 + ai * HALF + m * 16) * D + col0 + bj * HALF) = w;
;                         }
.LBB0_824:
	s_cmp_eq_u32 s51, 2
	s_cbranch_scc1 .Lem2_entry
	s_lshl_b32 s4, s51, 11
	s_cmp_eq_u32 s51, 2
	s_cselect_b64 s[20:21], -1, 0
	s_and_b64 s[22:23], s[20:21], exec
	v_lshl_add_u32 v168, s0, 8, v153
	s_cselect_b32 s0, 0, 0x800
	s_ashr_i32 s5, s4, 31
	s_lshl_b64 s[4:5], s[4:5], 1
	s_add_u32 s22, s40, s4
	v_lshl_or_b32 v166, s52, 8, v182
	s_addc_u32 s23, s41, s5
	v_ashrrev_i32_e32 v167, 31, v166
	v_mov_b64_e32 v[128:129], s[22:23]
	v_mad_i64_i32 v[130:131], s[4:5], v168, s46, v[128:129]
	v_lshlrev_b64 v[170:171], 1, v[166:167]
	v_lshl_add_u64 v[130:131], v[130:131], 0, v[170:171]
	v_add_co_u32_e32 v132, vcc, s37, v130
	s_lshl_b32 s0, s0, 1
	s_nop 0
	v_addc_co_u32_e32 v133, vcc, 0, v131, vcc
	v_lshl_add_u64 v[130:131], v[130:131], 0, s[12:13]
	v_lshl_add_u64 v[136:137], v[130:131], 0, s[0:1]
	global_load_dwordx4 v[184:187], v[132:133], off offset:2048
	global_load_dwordx4 v[148:151], v[130:131], off offset:256
	global_load_dwordx4 v[188:191], v[136:137], off
	v_or_b32_e32 v172, 16, v168
	v_mad_i64_i32 v[128:129], s[4:5], v172, s46, v[128:129]
	v_lshl_add_u64 v[128:129], v[128:129], 0, v[170:171]
	v_lshl_add_u64 v[132:133], v[128:129], 0, s[12:13]
	v_add_co_u32_e32 v128, vcc, s37, v128
	v_lshl_add_u64 v[130:131], v[132:133], 0, s[0:1]
	s_nop 0
	v_addc_co_u32_e32 v129, vcc, 0, v129, vcc
	global_load_dwordx4 v[140:143], v[128:129], off offset:2048
	s_nop 0
	global_load_dwordx4 v[132:135], v[132:133], off offset:256
	s_nop 0
	global_load_dwordx4 v[144:147], v[136:137], off offset:256
	s_nop 0
	global_load_dwordx4 v[136:139], v[130:131], off
	s_nop 0
	global_load_dwordx4 v[128:131], v[130:131], off offset:256
	v_ashrrev_i32_e32 v169, 31, v168
	v_lshlrev_b64 v[174:175], 12, v[168:169]
	v_lshl_add_u64 v[174:175], s[58:59], 0, v[174:175]
	s_cmp_lg_u32 s51, 2
	v_lshl_add_u64 v[174:175], v[166:167], 1, v[174:175]
	s_waitcnt vmcnt(0)
	v_lshlrev_b32_e32 v169, 16, v184
	v_and_b32_e32 v173, 0xffff0000, v184
	v_lshlrev_b32_e32 v184, 16, v185
	v_and_b32_e32 v192, 0xffff0000, v185
	v_lshlrev_b32_e32 v185, 16, v186
	v_and_b32_e32 v186, 0xffff0000, v186
	v_lshlrev_b32_e32 v193, 16, v187
	v_and_b32_e32 v194, 0xffff0000, v187
	v_lshlrev_b32_e32 v187, 16, v188
	v_lshlrev_b32_e32 v195, 16, v189
	v_lshlrev_b32_e32 v196, 16, v190
	v_and_b32_e32 v190, 0xffff0000, v190
	v_max_f32_e32 v198, 0x358637bd, v186
	v_max_f32_e32 v186, v190, v190
	v_max_f32_e32 v190, 0x358637bd, v184
	v_max_f32_e32 v187, 0x358637bd, v187
	v_max_f32_e32 v184, 0x358637bd, v195
	v_rcp_f32_e32 v187, v187
	v_rcp_f32_e32 v184, v184
	v_and_b32_e32 v188, 0xffff0000, v188
	v_and_b32_e32 v189, 0xffff0000, v189
	v_max_f32_e32 v169, 0x358637bd, v169
	v_max_f32_e32 v196, 0x358637bd, v196
	v_max_f32_e32 v188, 0x358637bd, v188
	v_cndmask_b32_e64 v187, v187, 1.0, s[20:21]
	v_max_f32_e32 v186, 0x358637bd, v186
	v_rcp_f32_e32 v196, v196
	v_rcp_f32_e32 v188, v188
	v_cndmask_b32_e64 v199, v184, 1.0, s[20:21]
	v_mul_f32_e32 v184, v169, v187
	v_lshlrev_b32_e32 v197, 16, v191
	v_and_b32_e32 v191, 0xffff0000, v191
	v_rcp_f32_e32 v186, v186
	v_max_f32_e32 v169, 0x358637bd, v189
	v_rcp_f32_e32 v169, v169
	v_max_f32_e32 v195, 0x358637bd, v197
	v_max_f32_e32 v189, 0x358637bd, v191
	v_max_f32_e32 v185, 0x358637bd, v185
	v_max_f32_e32 v173, 0x358637bd, v173
	v_rcp_f32_e32 v195, v195
	v_cndmask_b32_e64 v196, v196, 1.0, s[20:21]
	v_cndmask_b32_e64 v188, v188, 1.0, s[20:21]
	v_rcp_f32_e32 v191, v189
	v_cndmask_b32_e64 v197, v186, 1.0, s[20:21]
	v_mul_f32_e32 v186, v185, v196
	v_mul_f32_e32 v185, v173, v188
	v_max_f32_e32 v173, 0x358637bd, v192
	v_cndmask_b32_e64 v169, v169, 1.0, s[20:21]
	v_mul_f32_e32 v189, v173, v169
	v_max_f32_e32 v193, 0x358637bd, v193
	v_cndmask_b32_e64 v195, v195, 1.0, s[20:21]
	v_max_f32_e32 v169, 0x358637bd, v194
	v_cndmask_b32_e64 v173, v191, 1.0, s[20:21]
	v_mul_f32_e32 v187, v198, v197
	v_mul_f32_e32 v188, v190, v199
	v_mul_f32_e32 v190, v193, v195
	v_mul_f32_e32 v191, v169, v173
	v_pk_mul_f32 v[126:127], v[126:127], v[188:189]
	v_pk_mul_f32 v[124:125], v[124:125], v[184:185]
	v_pk_mul_f32 v[122:123], v[122:123], v[190:191]
	v_pk_mul_f32 v[120:121], v[120:121], v[186:187]
	s_cbranch_scc1 .LBB0_826
	v_cvt_pk_bf16_f32 v184, v124, v125
	v_cvt_pk_bf16_f32 v185, v126, v127
	v_cvt_pk_bf16_f32 v186, v120, v121
	v_cvt_pk_bf16_f32 v187, v122, v123
	global_store_dwordx4 v[174:175], v[184:187], off

; __device__ __forceinline__ unsigned cvt_pk_bf16(float lo, float hi) { unsigned r; asm volatile("v_cvt_pk_bf16_f32 %0, %1, %2" : "=v"(r) : "v"(lo), "v"(hi)); return r; }
; __device__ __forceinline__ float bflo(unsigned w) { return __uint_as_float(w << 16); }
; __device__ __forceinline__ float bfhi(unsigned w) { return __uint_as_float(w & 0xffff0000u); }
;     __device__ __forceinline__ void operator()(f32x4 (&acc)[2][2][4][2], const Unit& u, int wr, int wc, int fr, int fq) const {
;     ...
;                         const bf16_t* zp = Z + (size_t)(row0 + ai * HALF + (2 * m2 + mm) * 16) * NZ + koff + col0 + bj * HALF;
;                         ga[mm][bj] = *(const u32x4*)zp;
;                         gb[mm][bj] = *(const u32x4*)(zp + noff);
;                     }
; #pragma unroll
;                 for (int mm = 0; mm < 2; ++mm)
; #pragma unroll
;                     for (int bj = 0; bj < 2; ++bj) {
;                         const int m = 2 * m2 + mm;
;                         const u32x4 a4 = ga[mm][bj], b4 = gb[mm][bj];
;                         f32x4 g0 = (f32x4){bflo(a4.x), bfhi(a4.x), bflo(a4.y), bfhi(a4.y)}, g1 = (f32x4){bflo(a4.z), bfhi(a4.z), bflo(a4.w), bfhi(a4.w)};
;                         const f32x4 h0 = (f32x4){bflo(b4.x), bfhi(b4.x), bflo(b4.y), bfhi(b4.y)}, h1 = (f32x4){bflo(b4.z), bfhi(b4.z), bflo(b4.w), bfhi(b4.w)};
; #pragma unroll
;                         for (int j = 0; j < 4; ++j) {
;                             g0[j] = fmaxf(g0[j], 1e-6f) * (last ? 1.0f : __builtin_amdgcn_rcpf(fmaxf(h0[j], 1e-6f)));
;                             g1[j] = fmaxf(g1[j], 1e-6f) * (last ? 1.0f : __builtin_amdgcn_rcpf(fmaxf(h1[j], 1e-6f)));
;                         }
;                         acc[ai][bj][m][0] *= g0; acc[ai][bj][m][1] *= g1;
;                         if (last) {
;                             const f32x4 v0 = acc[ai][bj][m][0], v1 = acc[ai][bj][m][1];
;                             u32x4 w; w.x = cvt_pk_bf16(v0[0], v0[1]); w.y = cvt_pk_bf16(v0[2], v0[3]); w.z = cvt_pk_bf16(v1[0], v1[1]); w.w = cvt_pk_bf16(v1[2], v1[3]);
;                             *(u32x4*)(MB + (size_t)(row0 + ai * HALF + m * 16) * D + col0 + bj * HALF) = w;
.LBB0_854:
	v_lshlrev_b32_e32 v142, 16, v128
	v_and_b32_e32 v143, 0xffff0000, v128
	v_lshlrev_b32_e32 v144, 16, v129
	v_and_b32_e32 v145, 0xffff0000, v129
	v_lshlrev_b32_e32 v128, 16, v130
	v_and_b32_e32 v129, 0xffff0000, v130
	v_max_f32_e32 v130, 0x358637bd, v142
	s_waitcnt vmcnt(0)
	v_lshlrev_b32_e32 v138, 16, v132
	v_rcp_f32_e32 v130, v130
	v_max_f32_e32 v128, 0x358637bd, v128
	v_lshlrev_b32_e32 v146, 16, v131
	v_and_b32_e32 v142, 0xffff0000, v131
	v_max_f32_e32 v131, v138, v138
	v_rcp_f32_e32 v138, v128
	v_max_f32_e32 v131, 0x358637bd, v131
	v_cndmask_b32_e64 v130, v130, 1.0, s[20:21]
	v_mul_f32_e32 v128, v131, v130
	v_cndmask_b32_e64 v131, v138, 1.0, s[20:21]
	v_max_f32_e32 v138, 0x358637bd, v143
	v_rcp_f32_e32 v138, v138
	v_lshlrev_b32_e32 v140, 16, v134
	v_and_b32_e32 v132, 0xffff0000, v132
	v_max_f32_e32 v130, 0x358637bd, v140
	v_max_f32_e32 v129, 0x358637bd, v129
	v_mul_f32_e32 v130, v130, v131
	v_max_f32_e32 v131, v132, v132
	v_cndmask_b32_e64 v132, v138, 1.0, s[20:21]
	v_rcp_f32_e32 v138, v129
	v_and_b32_e32 v134, 0xffff0000, v134
	v_max_f32_e32 v131, 0x358637bd, v131
	v_mul_f32_e32 v129, v131, v132
	v_max_f32_e32 v131, v134, v134
	v_max_f32_e32 v134, 0x358637bd, v144
	v_lshlrev_b32_e32 v139, 16, v133
	v_max_f32_e32 v131, 0x358637bd, v131
	v_cndmask_b32_e64 v132, v138, 1.0, s[20:21]
	v_rcp_f32_e32 v134, v134
	v_mul_f32_e32 v131, v131, v132
	v_max_f32_e32 v132, v139, v139
	v_max_f32_e32 v138, 0x358637bd, v146
	v_rcp_f32_e32 v138, v138
	v_max_f32_e32 v139, 0x358637bd, v145
	v_rcp_f32_e32 v139, v139
	v_lshlrev_b32_e32 v141, 16, v135
	v_max_f32_e32 v132, 0x358637bd, v132
	v_cndmask_b32_e64 v134, v134, 1.0, s[20:21]
	v_mul_f32_e32 v132, v132, v134
	v_max_f32_e32 v134, 0x358637bd, v141
	v_cndmask_b32_e64 v138, v138, 1.0, s[20:21]
	v_mul_f32_e32 v134, v134, v138
	v_cndmask_b32_e64 v138, v139, 1.0, s[20:21]
	v_max_f32_e32 v139, 0x358637bd, v142
	v_rcp_f32_e32 v139, v139
	v_and_b32_e32 v133, 0xffff0000, v133
	v_and_b32_e32 v135, 0xffff0000, v135
	v_max_f32_e32 v133, 0x358637bd, v133
	v_mul_f32_e32 v133, v133, v138
	v_max_f32_e32 v135, 0x358637bd, v135
	v_cndmask_b32_e64 v138, v139, 1.0, s[20:21]
	v_mul_f32_e32 v135, v135, v138
	v_pk_mul_f32 v[6:7], v[6:7], v[132:133]
	v_pk_mul_f32 v[4:5], v[4:5], v[128:129]
	v_pk_mul_f32 v[2:3], v[2:3], v[134:135]
	s_and_b64 vcc, exec, s[4:5]
	v_pk_mul_f32 v[0:1], v[0:1], v[130:131]
	s_cbranch_vccnz .LBB0_856
	v_cvt_pk_bf16_f32 v128, v4, v5
	v_cvt_pk_bf16_f32 v129, v6, v7
	v_cvt_pk_bf16_f32 v130, v0, v1
	v_cvt_pk_bf16_f32 v131, v2, v3
	global_store_dwordx4 v[136:137], v[128:131], off offset:256
	s_branch .LBB0_856
.Lem2_entry:
	s_lshl_b32 s4, s51, 11
	s_cmp_eq_u32 s51, 2
	s_cselect_b64 s[20:21], -1, 0
	s_and_b64 s[22:23], s[20:21], exec
	v_lshl_add_u32 v168, s0, 8, v153
	s_cselect_b32 s0, 0, 0x800
	s_ashr_i32 s5, s4, 31
	s_lshl_b64 s[4:5], s[4:5], 1
	s_add_u32 s22, s40, s4
	v_lshl_or_b32 v166, s52, 8, v182
	s_addc_u32 s23, s41, s5
	v_ashrrev_i32_e32 v167, 31, v166
	v_mov_b64_e32 v[128:129], s[22:23]
	v_mad_i64_i32 v[130:131], s[4:5], v168, s46, v[128:129]
	v_lshlrev_b64 v[170:171], 1, v[166:167]
	v_lshl_add_u64 v[130:131], v[130:131], 0, v[170:171]
	v_add_co_u32_e32 v132, vcc, s37, v130
	s_lshl_b32 s0, s0, 1
	s_nop 0
	v_addc_co_u32_e32 v133, vcc, 0, v131, vcc
	v_lshl_add_u64 v[130:131], v[130:131], 0, s[12:13]
	v_lshl_add_u64 v[136:137], v[130:131], 0, s[0:1]
	global_load_dwordx4 v[184:187], v[132:133], off offset:2048
	global_load_dwordx4 v[148:151], v[130:131], off offset:256
	global_load_dwordx4 v[188:191], v[136:137], off
	v_or_b32_e32 v172, 16, v168
	v_mad_i64_i32 v[128:129], s[4:5], v172, s46, v[128:129]
	v_lshl_add_u64 v[128:129], v[128:129], 0, v[170:171]
	v_lshl_add_u64 v[132:133], v[128:129], 0, s[12:13]
	v_add_co_u32_e32 v128, vcc, s37, v128
	v_lshl_add_u64 v[130:131], v[132:133], 0, s[0:1]
	s_nop 0
	v_addc_co_u32_e32 v129, vcc, 0, v129, vcc
	global_load_dwordx4 v[140:143], v[128:129], off offset:2048
	s_nop 0
	global_load_dwordx4 v[132:135], v[132:133], off offset:256
	s_nop 0
	global_load_dwordx4 v[144:147], v[136:137], off offset:256
	s_nop 0
	global_load_dwordx4 v[136:139], v[130:131], off
	s_nop 0
	global_load_dwordx4 v[128:131], v[130:131], off offset:256
	v_ashrrev_i32_e32 v169, 31, v168
	v_lshlrev_b64 v[174:175], 12, v[168:169]
	v_lshl_add_u64 v[174:175], s[58:59], 0, v[174:175]
	s_cmp_lg_u32 s51, 2
	v_lshl_add_u64 v[174:175], v[166:167], 1, v[174:175]
	s_waitcnt vmcnt(0)
; __device__ __forceinline__ unsigned cvt_pk_bf16(float lo, float hi) { unsigned r; asm volatile("v_cvt_pk_bf16_f32 %0, %1, %2" : "=v"(r) : "v"(lo), "v"(hi)); return r; }
; __device__ __forceinline__ float bflo(unsigned w) { return __uint_as_float(w << 16); }
; __device__ __forceinline__ float bfhi(unsigned w) { return __uint_as_float(w & 0xffff0000u); }
;     __device__ __forceinline__ void operator()(f32x4 (&acc)[2][2][4][2], const Unit& u, int wr, int wc, int fr, int fq) const {
;     ...
;                 for (int mm = 0; mm < 2; ++mm)
; #pragma unroll
;                     for (int bj = 0; bj < 2; ++bj) {
;                         const int m = 2 * m2 + mm;
;                         const u32x4 a4 = ga[mm][bj], b4 = gb[mm][bj];
;                         f32x4 g0 = (f32x4){bflo(a4.x), bfhi(a4.x), bflo(a4.y), bfhi(a4.y)}, g1 = (f32x4){bflo(a4.z), bfhi(a4.z), bflo(a4.w), bfhi(a4.w)};
;                         const f32x4 h0 = (f32x4){bflo(b4.x), bfhi(b4.x), bflo(b4.y), bfhi(b4.y)}, h1 = (f32x4){bflo(b4.z), bfhi(b4.z), bflo(b4.w), bfhi(b4.w)};
; #pragma unroll
;                         for (int j = 0; j < 4; ++j) {
;                             g0[j] = fmaxf(g0[j], 1e-6f) * (last ? 1.0f : __builtin_amdgcn_rcpf(fmaxf(h0[j], 1e-6f)));
;                             g1[j] = fmaxf(g1[j], 1e-6f) * (last ? 1.0f : __builtin_amdgcn_rcpf(fmaxf(h1[j], 1e-6f)));
;                         }
;                         acc[ai][bj][m][0] *= g0; acc[ai][bj][m][1] *= g1;
;                         if (last) {
;                             const f32x4 v0 = acc[ai][bj][m][0], v1 = acc[ai][bj][m][1];
;                             u32x4 w; w.x = cvt_pk_bf16(v0[0], v0[1]); w.y = cvt_pk_bf16(v0[2], v0[3]); w.z = cvt_pk_bf16(v1[0], v1[1]); w.w = cvt_pk_bf16(v1[2], v1[3]);
;                             *(u32x4*)(MB + (size_t)(row0 + ai * HALF + m * 16) * D + col0 + bj * HALF) = w;
	v_lshlrev_b32_e32 v169, 16, v184
	v_and_b32_e32 v173, 0xffff0000, v184
	v_lshlrev_b32_e32 v184, 16, v185
	v_and_b32_e32 v192, 0xffff0000, v185
	v_lshlrev_b32_e32 v185, 16, v186
	v_and_b32_e32 v186, 0xffff0000, v186
	v_lshlrev_b32_e32 v193, 16, v187
	v_and_b32_e32 v194, 0xffff0000, v187
	v_max_f32_e32 v198, 0x358637bd, v186
	v_max_f32_e32 v190, 0x358637bd, v184
	v_max_f32_e32 v169, 0x358637bd, v169
	v_mov_b32_e32 v184, v169
	v_max_f32_e32 v185, 0x358637bd, v185
	v_max_f32_e32 v173, 0x358637bd, v173
	v_mov_b32_e32 v186, v185
	v_mov_b32_e32 v185, v173
	v_max_f32_e32 v173, 0x358637bd, v192
	v_mov_b32_e32 v189, v173
	v_max_f32_e32 v193, 0x358637bd, v193
	v_max_f32_e32 v169, 0x358637bd, v194
	v_mov_b32_e32 v187, v198
	v_mov_b32_e32 v188, v190
	v_mov_b32_e32 v190, v193
	v_mov_b32_e32 v191, v169
	v_pk_mul_f32 v[126:127], v[126:127], v[188:189]
	v_pk_mul_f32 v[124:125], v[124:125], v[184:185]
	v_pk_mul_f32 v[122:123], v[122:123], v[190:191]
	v_pk_mul_f32 v[120:121], v[120:121], v[186:187]
	v_cvt_pk_bf16_f32 v184, v124, v125
	v_cvt_pk_bf16_f32 v185, v126, v127
	v_cvt_pk_bf16_f32 v186, v120, v121
	v_cvt_pk_bf16_f32 v187, v122, v123
	global_store_dwordx4 v[174:175], v[184:187], off
	s_nop 1
	s_nop 1
	v_lshlrev_b32_e32 v169, 16, v148
	v_max_f32_e32 v147, v169, v169
	v_max_f32_e32 v147, 0x358637bd, v147
	v_mov_b32_e32 v144, v147
	v_lshlrev_b32_e32 v184, 16, v150
	v_and_b32_e32 v148, 0xffff0000, v148
	v_max_f32_e32 v146, 0x358637bd, v184
	v_max_f32_e32 v147, v148, v148
	v_and_b32_e32 v150, 0xffff0000, v150
	v_max_f32_e32 v147, 0x358637bd, v147
	v_mov_b32_e32 v145, v147
	v_max_f32_e32 v147, v150, v150
	v_lshlrev_b32_e32 v173, 16, v149
	v_max_f32_e32 v147, 0x358637bd, v147
	v_max_f32_e32 v148, v173, v173
	v_lshlrev_b32_e32 v185, 16, v151
	v_max_f32_e32 v148, 0x358637bd, v148
	v_max_f32_e32 v150, 0x358637bd, v185
	v_and_b32_e32 v149, 0xffff0000, v149
	v_and_b32_e32 v151, 0xffff0000, v151
	v_max_f32_e32 v149, 0x358637bd, v149
	v_max_f32_e32 v151, 0x358637bd, v151
	v_pk_mul_f32 v[92:93], v[92:93], v[144:145]
	v_cndmask_b32_e64 v144, 0, 1, s[20:21]
	v_pk_mul_f32 v[94:95], v[94:95], v[148:149]
	v_pk_mul_f32 v[90:91], v[90:91], v[150:151]
	v_cmp_ne_u32_e64 s[4:5], 1, v144
	s_andn2_b64 vcc, exec, s[20:21]
	v_pk_mul_f32 v[88:89], v[88:89], v[146:147]
	v_cvt_pk_bf16_f32 v144, v92, v93
	v_cvt_pk_bf16_f32 v145, v94, v95
	v_cvt_pk_bf16_f32 v146, v88, v89
	v_cvt_pk_bf16_f32 v147, v90, v91
	global_store_dwordx4 v[174:175], v[144:147], off offset:256
	s_nop 1
	v_ashrrev_i32_e32 v173, 31, v172
	v_lshlrev_b64 v[144:145], 12, v[172:173]
	v_lshlrev_b32_e32 v146, 16, v140
	v_max_f32_e32 v139, v146, v146
	v_max_f32_e32 v139, 0x358637bd, v139
	v_mov_b32_e32 v136, v139
	v_lshlrev_b32_e32 v148, 16, v142
	v_and_b32_e32 v140, 0xffff0000, v140
	v_max_f32_e32 v138, 0x358637bd, v148
	v_max_f32_e32 v139, v140, v140
	v_and_b32_e32 v142, 0xffff0000, v142
	v_max_f32_e32 v139, 0x358637bd, v139
	v_mov_b32_e32 v137, v139
	v_max_f32_e32 v139, v142, v142
	v_lshlrev_b32_e32 v147, 16, v141
	v_max_f32_e32 v139, 0x358637bd, v139
	v_max_f32_e32 v140, v147, v147
	v_lshlrev_b32_e32 v149, 16, v143
	v_max_f32_e32 v140, 0x358637bd, v140
	v_max_f32_e32 v142, 0x358637bd, v149
	v_and_b32_e32 v141, 0xffff0000, v141
	v_and_b32_e32 v143, 0xffff0000, v143
	v_max_f32_e32 v141, 0x358637bd, v141
	v_max_f32_e32 v143, 0x358637bd, v143
	v_pk_mul_f32 v[116:117], v[116:117], v[136:137]
	v_lshl_add_u64 v[136:137], s[58:59], 0, v[144:145]
	v_pk_mul_f32 v[118:119], v[118:119], v[140:141]
	v_pk_mul_f32 v[114:115], v[114:115], v[142:143]
	v_pk_mul_f32 v[112:113], v[112:113], v[138:139]
	s_and_b64 vcc, exec, s[4:5]
	v_lshl_add_u64 v[136:137], v[166:167], 1, v[136:137]
	v_cvt_pk_bf16_f32 v138, v116, v117
	v_cvt_pk_bf16_f32 v139, v118, v119
	v_cvt_pk_bf16_f32 v140, v112, v113
	v_cvt_pk_bf16_f32 v141, v114, v115
	global_store_dwordx4 v[136:137], v[138:141], off
	s_nop 1
	v_lshlrev_b32_e32 v138, 16, v132
	v_max_f32_e32 v131, v138, v138
	v_max_f32_e32 v131, 0x358637bd, v131
	v_mov_b32_e32 v128, v131
	v_lshlrev_b32_e32 v140, 16, v134
	v_and_b32_e32 v132, 0xffff0000, v132
	v_max_f32_e32 v130, 0x358637bd, v140
	v_max_f32_e32 v131, v132, v132
	v_and_b32_e32 v134, 0xffff0000, v134
	v_max_f32_e32 v131, 0x358637bd, v131
	v_mov_b32_e32 v129, v131
	v_max_f32_e32 v131, v134, v134
	v_lshlrev_b32_e32 v139, 16, v133
	v_max_f32_e32 v131, 0x358637bd, v131
	v_max_f32_e32 v132, v139, v139
	v_lshlrev_b32_e32 v141, 16, v135
	v_max_f32_e32 v132, 0x358637bd, v132
	v_max_f32_e32 v134, 0x358637bd, v141
	v_and_b32_e32 v133, 0xffff0000, v133
	v_and_b32_e32 v135, 0xffff0000, v135
	v_max_f32_e32 v133, 0x358637bd, v133
	v_max_f32_e32 v135, 0x358637bd, v135
	v_pk_mul_f32 v[86:87], v[86:87], v[132:133]
	v_pk_mul_f32 v[84:85], v[84:85], v[128:129]
	v_pk_mul_f32 v[82:83], v[82:83], v[134:135]
	s_and_b64 vcc, exec, s[4:5]
	v_pk_mul_f32 v[80:81], v[80:81], v[130:131]
	v_cvt_pk_bf16_f32 v128, v84, v85
	v_cvt_pk_bf16_f32 v129, v86, v87
	v_cvt_pk_bf16_f32 v130, v80, v81
	v_cvt_pk_bf16_f32 v131, v82, v83
	global_store_dwordx4 v[136:137], v[128:131], off offset:256
	s_nop 1
	s_nop 1
	v_or_b32_e32 v128, 32, v168
	v_mov_b64_e32 v[130:131], s[22:23]
	v_mad_i64_i32 v[132:133], s[24:25], v128, s46, v[130:131]
	v_lshl_add_u64 v[132:133], v[132:133], 0, v[170:171]
	v_add_co_u32_e32 v134, vcc, 0x2000, v132
	v_or_b32_e32 v172, 48, v168
	s_nop 0
	v_addc_co_u32_e32 v135, vcc, 0, v133, vcc
	v_lshl_add_u64 v[132:133], v[132:133], 0, s[12:13]
	global_load_dwordx4 v[184:187], v[134:135], off offset:2048
	v_lshl_add_u64 v[134:135], v[132:133], 0, s[0:1]
	global_load_dwordx4 v[188:191], v[134:135], off
	v_mad_i64_i32 v[130:131], s[24:25], v172, s46, v[130:131]
	v_lshl_add_u64 v[130:131], v[130:131], 0, v[170:171]
	v_ashrrev_i32_e32 v129, 31, v128
	v_lshl_add_u64 v[192:193], v[130:131], 0, s[12:13]
	v_add_co_u32_e32 v140, vcc, s37, v130
	v_lshlrev_b64 v[174:175], 12, v[128:129]
	v_lshl_add_u64 v[128:129], v[192:193], 0, s[0:1]
	v_addc_co_u32_e32 v141, vcc, 0, v131, vcc
	global_load_dwordx4 v[148:151], v[132:133], off offset:256
	global_load_dwordx4 v[144:147], v[134:135], off offset:256
	global_load_dwordx4 v[136:139], v[128:129], off
	s_nop 0
	global_load_dwordx4 v[128:131], v[128:129], off offset:256
	s_nop 0
	global_load_dwordx4 v[140:143], v[140:141], off offset:2048
	s_nop 0
	global_load_dwordx4 v[132:135], v[192:193], off offset:256
	v_lshl_add_u64 v[174:175], s[58:59], 0, v[174:175]
	s_and_b64 vcc, exec, s[4:5]
	v_lshl_add_u64 v[174:175], v[166:167], 1, v[174:175]
	s_waitcnt vmcnt(7)
; __device__ __forceinline__ unsigned cvt_pk_bf16(float lo, float hi) { unsigned r; asm volatile("v_cvt_pk_bf16_f32 %0, %1, %2" : "=v"(r) : "v"(lo), "v"(hi)); return r; }
; __device__ __forceinline__ float bflo(unsigned w) { return __uint_as_float(w << 16); }
; __device__ __forceinline__ float bfhi(unsigned w) { return __uint_as_float(w & 0xffff0000u); }
;     __device__ __forceinline__ void operator()(f32x4 (&acc)[2][2][4][2], const Unit& u, int wr, int wc, int fr, int fq) const {
;     ...
;                 for (int mm = 0; mm < 2; ++mm)
; #pragma unroll
;                     for (int bj = 0; bj < 2; ++bj) {
;                         const int m = 2 * m2 + mm;
;                         const u32x4 a4 = ga[mm][bj], b4 = gb[mm][bj];
;                         f32x4 g0 = (f32x4){bflo(a4.x), bfhi(a4.x), bflo(a4.y), bfhi(a4.y)}, g1 = (f32x4){bflo(a4.z), bfhi(a4.z), bflo(a4.w), bfhi(a4.w)};
;                         const f32x4 h0 = (f32x4){bflo(b4.x), bfhi(b4.x), bflo(b4.y), bfhi(b4.y)}, h1 = (f32x4){bflo(b4.z), bfhi(b4.z), bflo(b4.w), bfhi(b4.w)};
; #pragma unroll
;                         for (int j = 0; j < 4; ++j) {
;                             g0[j] = fmaxf(g0[j], 1e-6f) * (last ? 1.0f : __builtin_amdgcn_rcpf(fmaxf(h0[j], 1e-6f)));
;                             g1[j] = fmaxf(g1[j], 1e-6f) * (last ? 1.0f : __builtin_amdgcn_rcpf(fmaxf(h1[j], 1e-6f)));
;                         }
;                         acc[ai][bj][m][0] *= g0; acc[ai][bj][m][1] *= g1;
;                         if (last) {
;                             const f32x4 v0 = acc[ai][bj][m][0], v1 = acc[ai][bj][m][1];
;                             u32x4 w; w.x = cvt_pk_bf16(v0[0], v0[1]); w.y = cvt_pk_bf16(v0[2], v0[3]); w.z = cvt_pk_bf16(v1[0], v1[1]); w.w = cvt_pk_bf16(v1[2], v1[3]);
;                             *(u32x4*)(MB + (size_t)(row0 + ai * HALF + m * 16) * D + col0 + bj * HALF) = w;
	v_lshlrev_b32_e32 v193, 16, v187
	v_and_b32_e32 v194, 0xffff0000, v187
	s_waitcnt vmcnt(6)
	v_lshlrev_b32_e32 v169, 16, v184
	v_and_b32_e32 v173, 0xffff0000, v184
	v_lshlrev_b32_e32 v184, 16, v185
	v_and_b32_e32 v192, 0xffff0000, v185
	v_lshlrev_b32_e32 v185, 16, v186
	v_and_b32_e32 v186, 0xffff0000, v186
	v_max_f32_e32 v198, 0x358637bd, v186
	v_max_f32_e32 v190, 0x358637bd, v184
	v_max_f32_e32 v185, 0x358637bd, v185
	v_max_f32_e32 v173, 0x358637bd, v173
	v_mov_b32_e32 v186, v185
	v_mov_b32_e32 v185, v173
	v_max_f32_e32 v169, 0x358637bd, v169
	v_mov_b32_e32 v184, v169
	v_max_f32_e32 v169, 0x358637bd, v192
	v_mov_b32_e32 v189, v169
	v_max_f32_e32 v193, 0x358637bd, v193
	v_max_f32_e32 v169, 0x358637bd, v194
	v_mov_b32_e32 v187, v198
	v_mov_b32_e32 v188, v190
	v_mov_b32_e32 v190, v193
	v_mov_b32_e32 v191, v169
	v_pk_mul_f32 v[110:111], v[110:111], v[188:189]
	v_pk_mul_f32 v[108:109], v[108:109], v[184:185]
	v_pk_mul_f32 v[106:107], v[106:107], v[190:191]
	v_pk_mul_f32 v[104:105], v[104:105], v[186:187]
	v_cvt_pk_bf16_f32 v184, v108, v109
	v_cvt_pk_bf16_f32 v185, v110, v111
	v_cvt_pk_bf16_f32 v186, v104, v105
	v_cvt_pk_bf16_f32 v187, v106, v107
	global_store_dwordx4 v[174:175], v[184:187], off
	s_nop 1
	s_waitcnt vmcnt(4)
	s_nop 0
	v_lshlrev_b32_e32 v169, 16, v148
	v_max_f32_e32 v147, v169, v169
	v_max_f32_e32 v147, 0x358637bd, v147
	v_mov_b32_e32 v144, v147
	v_lshlrev_b32_e32 v184, 16, v150
	v_and_b32_e32 v148, 0xffff0000, v148
	v_max_f32_e32 v146, 0x358637bd, v184
	v_max_f32_e32 v147, v148, v148
	v_and_b32_e32 v150, 0xffff0000, v150
	v_max_f32_e32 v147, 0x358637bd, v147
	v_mov_b32_e32 v145, v147
	v_max_f32_e32 v147, v150, v150
	v_lshlrev_b32_e32 v173, 16, v149
	v_max_f32_e32 v147, 0x358637bd, v147
	v_max_f32_e32 v148, v173, v173
	v_lshlrev_b32_e32 v185, 16, v151
	v_max_f32_e32 v148, 0x358637bd, v148
	v_max_f32_e32 v150, 0x358637bd, v185
	v_and_b32_e32 v149, 0xffff0000, v149
	v_and_b32_e32 v151, 0xffff0000, v151
	v_max_f32_e32 v149, 0x358637bd, v149
	v_max_f32_e32 v151, 0x358637bd, v151
	v_pk_mul_f32 v[78:79], v[78:79], v[148:149]
	v_pk_mul_f32 v[76:77], v[76:77], v[144:145]
	v_pk_mul_f32 v[74:75], v[74:75], v[150:151]
	s_and_b64 vcc, exec, s[4:5]
	v_pk_mul_f32 v[72:73], v[72:73], v[146:147]
	v_cvt_pk_bf16_f32 v144, v76, v77
	v_cvt_pk_bf16_f32 v145, v78, v79
	v_cvt_pk_bf16_f32 v146, v72, v73
	v_cvt_pk_bf16_f32 v147, v74, v75
	global_store_dwordx4 v[174:175], v[144:147], off offset:256
	s_nop 1
	v_ashrrev_i32_e32 v173, 31, v172
	s_waitcnt vmcnt(3)
	v_lshlrev_b64 v[144:145], 12, v[172:173]
	s_waitcnt vmcnt(1)
	v_lshlrev_b32_e32 v146, 16, v140
	v_max_f32_e32 v139, v146, v146
	v_max_f32_e32 v139, 0x358637bd, v139
	v_mov_b32_e32 v136, v139
	v_lshlrev_b32_e32 v148, 16, v142
	v_and_b32_e32 v140, 0xffff0000, v140
	v_max_f32_e32 v138, 0x358637bd, v148
	v_max_f32_e32 v139, v140, v140
	v_and_b32_e32 v142, 0xffff0000, v142
	v_max_f32_e32 v139, 0x358637bd, v139
	v_mov_b32_e32 v137, v139
	v_max_f32_e32 v139, v142, v142
	v_lshlrev_b32_e32 v147, 16, v141
	v_max_f32_e32 v139, 0x358637bd, v139
	v_max_f32_e32 v140, v147, v147
	v_lshlrev_b32_e32 v149, 16, v143
	v_max_f32_e32 v140, 0x358637bd, v140
	v_max_f32_e32 v142, 0x358637bd, v149
	v_and_b32_e32 v141, 0xffff0000, v141
	v_and_b32_e32 v143, 0xffff0000, v143
	v_max_f32_e32 v141, 0x358637bd, v141
	v_max_f32_e32 v143, 0x358637bd, v143
	v_pk_mul_f32 v[100:101], v[100:101], v[136:137]
	v_lshl_add_u64 v[136:137], s[58:59], 0, v[144:145]
	v_pk_mul_f32 v[102:103], v[102:103], v[140:141]
	v_pk_mul_f32 v[98:99], v[98:99], v[142:143]
	v_pk_mul_f32 v[96:97], v[96:97], v[138:139]
	s_and_b64 vcc, exec, s[4:5]
	v_lshl_add_u64 v[136:137], v[166:167], 1, v[136:137]
	v_cvt_pk_bf16_f32 v138, v100, v101
	v_cvt_pk_bf16_f32 v139, v102, v103
	v_cvt_pk_bf16_f32 v140, v96, v97
	v_cvt_pk_bf16_f32 v141, v98, v99
	global_store_dwordx4 v[136:137], v[138:141], off
	s_nop 1
	s_waitcnt vmcnt(0)
	v_lshlrev_b32_e32 v138, 16, v132
	v_max_f32_e32 v131, v138, v138
	v_max_f32_e32 v131, 0x358637bd, v131
	v_mov_b32_e32 v128, v131
	v_lshlrev_b32_e32 v140, 16, v134
	v_and_b32_e32 v132, 0xffff0000, v132
	v_max_f32_e32 v130, 0x358637bd, v140
	v_max_f32_e32 v131, v132, v132
	v_and_b32_e32 v134, 0xffff0000, v134
	v_max_f32_e32 v131, 0x358637bd, v131
	v_mov_b32_e32 v129, v131
	v_max_f32_e32 v131, v134, v134
	v_lshlrev_b32_e32 v139, 16, v133
	v_max_f32_e32 v131, 0x358637bd, v131
	v_max_f32_e32 v132, v139, v139
	v_lshlrev_b32_e32 v141, 16, v135
	v_max_f32_e32 v132, 0x358637bd, v132
	v_max_f32_e32 v134, 0x358637bd, v141
	v_and_b32_e32 v133, 0xffff0000, v133
	v_and_b32_e32 v135, 0xffff0000, v135
	v_max_f32_e32 v133, 0x358637bd, v133
	v_max_f32_e32 v135, 0x358637bd, v135
	v_pk_mul_f32 v[70:71], v[70:71], v[132:133]
	v_pk_mul_f32 v[68:69], v[68:69], v[128:129]
	v_pk_mul_f32 v[66:67], v[66:67], v[134:135]
	s_and_b64 vcc, exec, s[4:5]
	v_pk_mul_f32 v[64:65], v[64:65], v[130:131]
	v_cvt_pk_bf16_f32 v128, v68, v69
	v_cvt_pk_bf16_f32 v129, v70, v71
	v_cvt_pk_bf16_f32 v130, v64, v65
	v_cvt_pk_bf16_f32 v131, v66, v67
	global_store_dwordx4 v[136:137], v[128:131], off offset:256
	s_nop 1
	s_nop 1
	v_add_u32_e32 v128, 0x80, v168
	v_mov_b64_e32 v[130:131], s[22:23]
	v_mad_i64_i32 v[132:133], s[24:25], v128, s46, v[130:131]
	v_lshl_add_u64 v[132:133], v[132:133], 0, v[170:171]
	v_add_co_u32_e32 v134, vcc, 0x2000, v132
	v_add_u32_e32 v172, 0x90, v168
	s_nop 0
	v_addc_co_u32_e32 v135, vcc, 0, v133, vcc
	v_lshl_add_u64 v[132:133], v[132:133], 0, s[12:13]
	global_load_dwordx4 v[184:187], v[134:135], off offset:2048
	v_lshl_add_u64 v[134:135], v[132:133], 0, s[0:1]
	global_load_dwordx4 v[188:191], v[134:135], off
	v_mad_i64_i32 v[130:131], s[24:25], v172, s46, v[130:131]
	v_lshl_add_u64 v[130:131], v[130:131], 0, v[170:171]
	v_ashrrev_i32_e32 v129, 31, v128
	v_lshl_add_u64 v[192:193], v[130:131], 0, s[12:13]
	v_add_co_u32_e32 v140, vcc, s37, v130
	v_lshlrev_b64 v[174:175], 12, v[128:129]
	v_lshl_add_u64 v[128:129], v[192:193], 0, s[0:1]
	v_addc_co_u32_e32 v141, vcc, 0, v131, vcc
	global_load_dwordx4 v[148:151], v[132:133], off offset:256
	global_load_dwordx4 v[144:147], v[134:135], off offset:256
	global_load_dwordx4 v[136:139], v[128:129], off
	s_nop 0
	global_load_dwordx4 v[128:131], v[128:129], off offset:256
	s_nop 0
	global_load_dwordx4 v[140:143], v[140:141], off offset:2048
	s_nop 0
	global_load_dwordx4 v[132:135], v[192:193], off offset:256
	v_lshl_add_u64 v[174:175], s[58:59], 0, v[174:175]
	s_and_b64 vcc, exec, s[4:5]
	v_lshl_add_u64 v[174:175], v[166:167], 1, v[174:175]
	s_waitcnt vmcnt(7)
; __device__ __forceinline__ unsigned cvt_pk_bf16(float lo, float hi) { unsigned r; asm volatile("v_cvt_pk_bf16_f32 %0, %1, %2" : "=v"(r) : "v"(lo), "v"(hi)); return r; }
; __device__ __forceinline__ float bflo(unsigned w) { return __uint_as_float(w << 16); }
; __device__ __forceinline__ float bfhi(unsigned w) { return __uint_as_float(w & 0xffff0000u); }
;     __device__ __forceinline__ void operator()(f32x4 (&acc)[2][2][4][2], const Unit& u, int wr, int wc, int fr, int fq) const {
;     ...
;                 for (int mm = 0; mm < 2; ++mm)
; #pragma unroll
;                     for (int bj = 0; bj < 2; ++bj) {
;                         const int m = 2 * m2 + mm;
;                         const u32x4 a4 = ga[mm][bj], b4 = gb[mm][bj];
;                         f32x4 g0 = (f32x4){bflo(a4.x), bfhi(a4.x), bflo(a4.y), bfhi(a4.y)}, g1 = (f32x4){bflo(a4.z), bfhi(a4.z), bflo(a4.w), bfhi(a4.w)};
;                         const f32x4 h0 = (f32x4){bflo(b4.x), bfhi(b4.x), bflo(b4.y), bfhi(b4.y)}, h1 = (f32x4){bflo(b4.z), bfhi(b4.z), bflo(b4.w), bfhi(b4.w)};
; #pragma unroll
;                         for (int j = 0; j < 4; ++j) {
;                             g0[j] = fmaxf(g0[j], 1e-6f) * (last ? 1.0f : __builtin_amdgcn_rcpf(fmaxf(h0[j], 1e-6f)));
;                             g1[j] = fmaxf(g1[j], 1e-6f) * (last ? 1.0f : __builtin_amdgcn_rcpf(fmaxf(h1[j], 1e-6f)));
;                         }
;                         acc[ai][bj][m][0] *= g0; acc[ai][bj][m][1] *= g1;
;                         if (last) {
;                             const f32x4 v0 = acc[ai][bj][m][0], v1 = acc[ai][bj][m][1];
;                             u32x4 w; w.x = cvt_pk_bf16(v0[0], v0[1]); w.y = cvt_pk_bf16(v0[2], v0[3]); w.z = cvt_pk_bf16(v1[0], v1[1]); w.w = cvt_pk_bf16(v1[2], v1[3]);
;                             *(u32x4*)(MB + (size_t)(row0 + ai * HALF + m * 16) * D + col0 + bj * HALF) = w;
	v_lshlrev_b32_e32 v193, 16, v187
	v_and_b32_e32 v194, 0xffff0000, v187
	s_waitcnt vmcnt(6)
	v_lshlrev_b32_e32 v169, 16, v184
	v_and_b32_e32 v173, 0xffff0000, v184
	v_lshlrev_b32_e32 v184, 16, v185
	v_and_b32_e32 v192, 0xffff0000, v185
	v_lshlrev_b32_e32 v185, 16, v186
	v_and_b32_e32 v186, 0xffff0000, v186
	v_max_f32_e32 v198, 0x358637bd, v186
	v_max_f32_e32 v190, 0x358637bd, v184
	v_max_f32_e32 v185, 0x358637bd, v185
	v_max_f32_e32 v173, 0x358637bd, v173
	v_mov_b32_e32 v197, 1.0
	v_mov_b32_e32 v186, v185
	v_mov_b32_e32 v185, v173
	v_max_f32_e32 v169, 0x358637bd, v169
	v_mov_b32_e32 v199, 1.0
	v_mov_b32_e32 v184, v169
	v_max_f32_e32 v169, 0x358637bd, v192
	v_mov_b32_e32 v189, v169
	v_max_f32_e32 v193, 0x358637bd, v193
	v_max_f32_e32 v169, 0x358637bd, v194
	v_mov_b32_e32 v187, v198
	v_mov_b32_e32 v188, v190
	v_mov_b32_e32 v190, v193
	v_mov_b32_e32 v191, v169
	v_pk_mul_f32 v[62:63], v[62:63], v[188:189]
	v_pk_mul_f32 v[60:61], v[60:61], v[184:185]
	v_pk_mul_f32 v[58:59], v[58:59], v[190:191]
	v_pk_mul_f32 v[56:57], v[56:57], v[186:187]
	v_cvt_pk_bf16_f32 v184, v60, v61
	v_cvt_pk_bf16_f32 v185, v62, v63
	v_cvt_pk_bf16_f32 v186, v56, v57
	v_cvt_pk_bf16_f32 v187, v58, v59
	global_store_dwordx4 v[174:175], v[184:187], off
	s_nop 1
	s_waitcnt vmcnt(4)
	s_nop 0
	v_lshlrev_b32_e32 v169, 16, v148
	v_max_f32_e32 v147, v169, v169
	v_max_f32_e32 v147, 0x358637bd, v147
	v_mov_b32_e32 v144, v147
	v_lshlrev_b32_e32 v184, 16, v150
	v_and_b32_e32 v148, 0xffff0000, v148
	v_max_f32_e32 v146, 0x358637bd, v184
	v_max_f32_e32 v147, v148, v148
	v_and_b32_e32 v150, 0xffff0000, v150
	v_max_f32_e32 v147, 0x358637bd, v147
	v_mov_b32_e32 v145, v147
	v_max_f32_e32 v147, v150, v150
	v_lshlrev_b32_e32 v173, 16, v149
	v_max_f32_e32 v147, 0x358637bd, v147
	v_max_f32_e32 v148, v173, v173
	v_lshlrev_b32_e32 v185, 16, v151
	v_max_f32_e32 v148, 0x358637bd, v148
	v_max_f32_e32 v150, 0x358637bd, v185
	v_and_b32_e32 v149, 0xffff0000, v149
	v_and_b32_e32 v151, 0xffff0000, v151
	v_max_f32_e32 v149, 0x358637bd, v149
	v_max_f32_e32 v151, 0x358637bd, v151
	v_pk_mul_f32 v[30:31], v[30:31], v[148:149]
	v_pk_mul_f32 v[28:29], v[28:29], v[144:145]
	v_pk_mul_f32 v[26:27], v[26:27], v[150:151]
	s_and_b64 vcc, exec, s[4:5]
	v_pk_mul_f32 v[24:25], v[24:25], v[146:147]
	v_cvt_pk_bf16_f32 v144, v28, v29
	v_cvt_pk_bf16_f32 v145, v30, v31
	v_cvt_pk_bf16_f32 v146, v24, v25
	v_cvt_pk_bf16_f32 v147, v26, v27
	global_store_dwordx4 v[174:175], v[144:147], off offset:256
	s_nop 1
	v_ashrrev_i32_e32 v173, 31, v172
	s_waitcnt vmcnt(3)
	v_lshlrev_b64 v[144:145], 12, v[172:173]
	s_waitcnt vmcnt(1)
	v_lshlrev_b32_e32 v146, 16, v140
	v_max_f32_e32 v139, v146, v146
	v_max_f32_e32 v139, 0x358637bd, v139
	v_mov_b32_e32 v136, v139
	v_lshlrev_b32_e32 v148, 16, v142
	v_and_b32_e32 v140, 0xffff0000, v140
	v_max_f32_e32 v138, 0x358637bd, v148
	v_max_f32_e32 v139, v140, v140
	v_and_b32_e32 v142, 0xffff0000, v142
	v_max_f32_e32 v139, 0x358637bd, v139
	v_mov_b32_e32 v137, v139
	v_max_f32_e32 v139, v142, v142
	v_lshlrev_b32_e32 v147, 16, v141
	v_max_f32_e32 v139, 0x358637bd, v139
	v_max_f32_e32 v140, v147, v147
	v_lshlrev_b32_e32 v149, 16, v143
	v_max_f32_e32 v140, 0x358637bd, v140
	v_max_f32_e32 v142, 0x358637bd, v149
	v_and_b32_e32 v141, 0xffff0000, v141
	v_and_b32_e32 v143, 0xffff0000, v143
	v_max_f32_e32 v141, 0x358637bd, v141
	v_max_f32_e32 v143, 0x358637bd, v143
	v_pk_mul_f32 v[52:53], v[52:53], v[136:137]
	v_lshl_add_u64 v[136:137], s[58:59], 0, v[144:145]
	v_pk_mul_f32 v[54:55], v[54:55], v[140:141]
	v_pk_mul_f32 v[50:51], v[50:51], v[142:143]
	v_pk_mul_f32 v[48:49], v[48:49], v[138:139]
	s_and_b64 vcc, exec, s[4:5]
	v_lshl_add_u64 v[136:137], v[166:167], 1, v[136:137]
	v_cvt_pk_bf16_f32 v138, v52, v53
	v_cvt_pk_bf16_f32 v139, v54, v55
	v_cvt_pk_bf16_f32 v140, v48, v49
	v_cvt_pk_bf16_f32 v141, v50, v51
	global_store_dwordx4 v[136:137], v[138:141], off
	s_nop 1
	s_waitcnt vmcnt(0)
	v_lshlrev_b32_e32 v138, 16, v132
	v_max_f32_e32 v131, v138, v138
	v_max_f32_e32 v131, 0x358637bd, v131
	v_mov_b32_e32 v128, v131
	v_lshlrev_b32_e32 v140, 16, v134
	v_and_b32_e32 v132, 0xffff0000, v132
	v_max_f32_e32 v130, 0x358637bd, v140
	v_max_f32_e32 v131, v132, v132
	v_and_b32_e32 v134, 0xffff0000, v134
	v_max_f32_e32 v131, 0x358637bd, v131
	v_mov_b32_e32 v129, v131
	v_max_f32_e32 v131, v134, v134
	v_lshlrev_b32_e32 v139, 16, v133
	v_max_f32_e32 v131, 0x358637bd, v131
	v_max_f32_e32 v132, v139, v139
	v_lshlrev_b32_e32 v141, 16, v135
	v_max_f32_e32 v132, 0x358637bd, v132
	v_max_f32_e32 v134, 0x358637bd, v141
	v_and_b32_e32 v133, 0xffff0000, v133
	v_and_b32_e32 v135, 0xffff0000, v135
	v_max_f32_e32 v133, 0x358637bd, v133
	v_max_f32_e32 v135, 0x358637bd, v135
	v_pk_mul_f32 v[22:23], v[22:23], v[132:133]
	v_pk_mul_f32 v[20:21], v[20:21], v[128:129]
	v_pk_mul_f32 v[18:19], v[18:19], v[134:135]
	s_and_b64 vcc, exec, s[4:5]
	v_pk_mul_f32 v[16:17], v[16:17], v[130:131]
	v_cvt_pk_bf16_f32 v128, v20, v21
	v_cvt_pk_bf16_f32 v129, v22, v23
	v_cvt_pk_bf16_f32 v130, v16, v17
	v_cvt_pk_bf16_f32 v131, v18, v19
	global_store_dwordx4 v[136:137], v[128:131], off offset:256
	s_nop 1
	s_nop 1
	v_add_u32_e32 v128, 0xa0, v168
	v_mov_b64_e32 v[130:131], s[22:23]
	v_mad_i64_i32 v[132:133], s[22:23], v128, s46, v[130:131]
	v_lshl_add_u64 v[132:133], v[132:133], 0, v[170:171]
	v_add_co_u32_e32 v134, vcc, 0x2000, v132
	v_add_u32_e32 v168, 0xb0, v168
	s_nop 0
	v_addc_co_u32_e32 v135, vcc, 0, v133, vcc
	v_lshl_add_u64 v[132:133], v[132:133], 0, s[12:13]
	global_load_dwordx4 v[172:175], v[134:135], off offset:2048
	v_lshl_add_u64 v[134:135], v[132:133], 0, s[0:1]
	global_load_dwordx4 v[184:187], v[134:135], off
	v_mad_i64_i32 v[130:131], s[22:23], v168, s46, v[130:131]
	v_lshl_add_u64 v[130:131], v[130:131], 0, v[170:171]
	v_ashrrev_i32_e32 v129, 31, v128
	v_lshl_add_u64 v[188:189], v[130:131], 0, s[12:13]
	v_add_co_u32_e32 v140, vcc, s37, v130
	v_lshlrev_b64 v[170:171], 12, v[128:129]
	v_lshl_add_u64 v[128:129], v[188:189], 0, s[0:1]
	v_addc_co_u32_e32 v141, vcc, 0, v131, vcc
	global_load_dwordx4 v[148:151], v[132:133], off offset:256
	global_load_dwordx4 v[144:147], v[134:135], off offset:256
	global_load_dwordx4 v[136:139], v[128:129], off
	s_nop 0
	global_load_dwordx4 v[128:131], v[128:129], off offset:256
	s_nop 0
	global_load_dwordx4 v[140:143], v[140:141], off offset:2048
	s_nop 0
	global_load_dwordx4 v[132:135], v[188:189], off offset:256
	v_lshl_add_u64 v[170:171], s[58:59], 0, v[170:171]
	s_and_b64 vcc, exec, s[4:5]
	v_lshl_add_u64 v[170:171], v[166:167], 1, v[170:171]
	s_waitcnt vmcnt(7)
; __device__ __forceinline__ unsigned cvt_pk_bf16(float lo, float hi) { unsigned r; asm volatile("v_cvt_pk_bf16_f32 %0, %1, %2" : "=v"(r) : "v"(lo), "v"(hi)); return r; }
; __device__ __forceinline__ float bflo(unsigned w) { return __uint_as_float(w << 16); }
; __device__ __forceinline__ float bfhi(unsigned w) { return __uint_as_float(w & 0xffff0000u); }
;     __device__ __forceinline__ void operator()(f32x4 (&acc)[2][2][4][2], const Unit& u, int wr, int wc, int fr, int fq) const {
;     ...
;                 for (int mm = 0; mm < 2; ++mm)
; #pragma unroll
;                     for (int bj = 0; bj < 2; ++bj) {
;                         const int m = 2 * m2 + mm;
;                         const u32x4 a4 = ga[mm][bj], b4 = gb[mm][bj];
;                         f32x4 g0 = (f32x4){bflo(a4.x), bfhi(a4.x), bflo(a4.y), bfhi(a4.y)}, g1 = (f32x4){bflo(a4.z), bfhi(a4.z), bflo(a4.w), bfhi(a4.w)};
;                         const f32x4 h0 = (f32x4){bflo(b4.x), bfhi(b4.x), bflo(b4.y), bfhi(b4.y)}, h1 = (f32x4){bflo(b4.z), bfhi(b4.z), bflo(b4.w), bfhi(b4.w)};
; #pragma unroll
;                         for (int j = 0; j < 4; ++j) {
;                             g0[j] = fmaxf(g0[j], 1e-6f) * (last ? 1.0f : __builtin_amdgcn_rcpf(fmaxf(h0[j], 1e-6f)));
;                             g1[j] = fmaxf(g1[j], 1e-6f) * (last ? 1.0f : __builtin_amdgcn_rcpf(fmaxf(h1[j], 1e-6f)));
;                         }
;                         acc[ai][bj][m][0] *= g0; acc[ai][bj][m][1] *= g1;
;                         if (last) {
;                             const f32x4 v0 = acc[ai][bj][m][0], v1 = acc[ai][bj][m][1];
;                             u32x4 w; w.x = cvt_pk_bf16(v0[0], v0[1]); w.y = cvt_pk_bf16(v0[2], v0[3]); w.z = cvt_pk_bf16(v1[0], v1[1]); w.w = cvt_pk_bf16(v1[2], v1[3]);
;                             *(u32x4*)(MB + (size_t)(row0 + ai * HALF + m * 16) * D + col0 + bj * HALF) = w;
	v_lshlrev_b32_e32 v190, 16, v175
	v_and_b32_e32 v191, 0xffff0000, v175
	s_waitcnt vmcnt(6)
	v_lshlrev_b32_e32 v169, 16, v172
	v_and_b32_e32 v172, 0xffff0000, v172
	v_max_f32_e32 v195, 0x358637bd, v172
	v_lshlrev_b32_e32 v188, 16, v173
	v_and_b32_e32 v189, 0xffff0000, v173
	v_lshlrev_b32_e32 v173, 16, v174
	v_and_b32_e32 v174, 0xffff0000, v174
	v_max_f32_e32 v184, 0x358637bd, v174
	v_max_f32_e32 v186, 0x358637bd, v188
	v_max_f32_e32 v169, 0x358637bd, v169
	v_mov_b32_e32 v194, 1.0
	v_mov_b32_e32 v172, v169
	v_max_f32_e32 v169, 0x358637bd, v189
	v_mov_b32_e32 v185, v169
	v_max_f32_e32 v173, 0x358637bd, v173
	v_max_f32_e32 v190, 0x358637bd, v190
	v_mov_b32_e32 v193, 1.0
	v_mov_b32_e32 v196, 1.0
	v_mov_b32_e32 v188, 1.0
	v_mov_b32_e32 v192, 1.0
	v_max_f32_e32 v169, 0x358637bd, v191
	v_mov_b32_e32 v174, v173
	v_mov_b32_e32 v173, v195
	v_mov_b32_e32 v175, v184
	v_mov_b32_e32 v184, v186
	v_mov_b32_e32 v186, v190
	v_mov_b32_e32 v187, v169
	v_pk_mul_f32 v[46:47], v[46:47], v[184:185]
	v_pk_mul_f32 v[44:45], v[44:45], v[172:173]
	v_pk_mul_f32 v[42:43], v[42:43], v[186:187]
	v_pk_mul_f32 v[40:41], v[40:41], v[174:175]
	v_cvt_pk_bf16_f32 v172, v44, v45
	v_cvt_pk_bf16_f32 v173, v46, v47
	v_cvt_pk_bf16_f32 v174, v40, v41
	v_cvt_pk_bf16_f32 v175, v42, v43
	global_store_dwordx4 v[170:171], v[172:175], off
	s_nop 1
	s_waitcnt vmcnt(4)
	s_nop 0
	v_and_b32_e32 v184, 0xffff0000, v144
	v_lshlrev_b32_e32 v185, 16, v145
	v_and_b32_e32 v186, 0xffff0000, v145
	v_lshlrev_b32_e32 v169, 16, v148
	v_lshlrev_b32_e32 v187, 16, v147
	v_and_b32_e32 v175, 0xffff0000, v147
	v_max_f32_e32 v147, v169, v169
	v_max_f32_e32 v147, 0x358637bd, v147
	v_mov_b32_e32 v144, v147
	v_lshlrev_b32_e32 v173, 16, v150
	v_and_b32_e32 v148, 0xffff0000, v148
	v_max_f32_e32 v146, 0x358637bd, v173
	v_max_f32_e32 v147, v148, v148
	v_and_b32_e32 v150, 0xffff0000, v150
	v_max_f32_e32 v147, 0x358637bd, v147
	v_mov_b32_e32 v145, v147
	v_max_f32_e32 v147, v150, v150
	v_lshlrev_b32_e32 v172, 16, v149
	v_max_f32_e32 v147, 0x358637bd, v147
	v_max_f32_e32 v148, v172, v172
	v_lshlrev_b32_e32 v174, 16, v151
	v_max_f32_e32 v148, 0x358637bd, v148
	v_max_f32_e32 v150, 0x358637bd, v174
	v_max_f32_e32 v172, 0x358637bd, v175
	v_rcp_f32_e32 v172, v172
	v_and_b32_e32 v149, 0xffff0000, v149
	v_and_b32_e32 v151, 0xffff0000, v151
	v_max_f32_e32 v149, 0x358637bd, v149
	v_max_f32_e32 v151, 0x358637bd, v151
	v_pk_mul_f32 v[14:15], v[14:15], v[148:149]
	v_pk_mul_f32 v[12:13], v[12:13], v[144:145]
	v_pk_mul_f32 v[10:11], v[10:11], v[150:151]
	s_and_b64 vcc, exec, s[4:5]
	v_pk_mul_f32 v[8:9], v[8:9], v[146:147]
	v_cvt_pk_bf16_f32 v144, v12, v13
	v_cvt_pk_bf16_f32 v145, v14, v15
	v_cvt_pk_bf16_f32 v146, v8, v9
	v_cvt_pk_bf16_f32 v147, v10, v11
	global_store_dwordx4 v[170:171], v[144:147], off offset:256
	s_nop 1
	v_ashrrev_i32_e32 v169, 31, v168
	s_waitcnt vmcnt(3)
	v_lshlrev_b64 v[144:145], 12, v[168:169]
	v_and_b32_e32 v151, 0xffff0000, v136
	v_lshlrev_b32_e32 v168, 16, v137
	v_and_b32_e32 v169, 0xffff0000, v137
	s_waitcnt vmcnt(1)
	v_lshlrev_b32_e32 v146, 16, v140
	v_lshlrev_b32_e32 v170, 16, v139
	v_and_b32_e32 v150, 0xffff0000, v139
	v_max_f32_e32 v139, v146, v146
	v_max_f32_e32 v139, 0x358637bd, v139
	v_mov_b32_e32 v136, v139
	v_lshlrev_b32_e32 v148, 16, v142
	v_and_b32_e32 v140, 0xffff0000, v140
	v_max_f32_e32 v138, 0x358637bd, v148
	v_max_f32_e32 v139, v140, v140
	v_and_b32_e32 v142, 0xffff0000, v142
	v_max_f32_e32 v139, 0x358637bd, v139
	v_mov_b32_e32 v137, v139
	v_max_f32_e32 v139, v142, v142
	v_lshlrev_b32_e32 v147, 16, v141
	v_max_f32_e32 v139, 0x358637bd, v139
	v_max_f32_e32 v140, v147, v147
	v_lshlrev_b32_e32 v149, 16, v143
	v_max_f32_e32 v140, 0x358637bd, v140
	v_max_f32_e32 v142, 0x358637bd, v149
	v_max_f32_e32 v147, 0x358637bd, v150
	v_rcp_f32_e32 v147, v147
	v_and_b32_e32 v141, 0xffff0000, v141
	v_and_b32_e32 v143, 0xffff0000, v143
	v_max_f32_e32 v141, 0x358637bd, v141
	v_max_f32_e32 v143, 0x358637bd, v143
	v_pk_mul_f32 v[36:37], v[36:37], v[136:137]
	v_lshl_add_u64 v[136:137], s[58:59], 0, v[144:145]
	v_pk_mul_f32 v[38:39], v[38:39], v[140:141]
	v_pk_mul_f32 v[34:35], v[34:35], v[142:143]
	v_pk_mul_f32 v[32:33], v[32:33], v[138:139]
	s_and_b64 vcc, exec, s[4:5]
	v_lshl_add_u64 v[136:137], v[166:167], 1, v[136:137]
	v_cvt_pk_bf16_f32 v138, v36, v37
	v_cvt_pk_bf16_f32 v139, v38, v39
	v_cvt_pk_bf16_f32 v140, v32, v33
	v_cvt_pk_bf16_f32 v141, v34, v35
	global_store_dwordx4 v[136:137], v[138:141], off
	s_nop 1
	v_and_b32_e32 v143, 0xffff0000, v128
	v_lshlrev_b32_e32 v144, 16, v129
	v_and_b32_e32 v145, 0xffff0000, v129
	s_waitcnt vmcnt(0)
	v_lshlrev_b32_e32 v138, 16, v132
	v_lshlrev_b32_e32 v146, 16, v131
	v_and_b32_e32 v142, 0xffff0000, v131
	v_max_f32_e32 v131, v138, v138
	v_max_f32_e32 v131, 0x358637bd, v131
	v_mov_b32_e32 v128, v131
	v_lshlrev_b32_e32 v140, 16, v134
	v_and_b32_e32 v132, 0xffff0000, v132
	v_max_f32_e32 v130, 0x358637bd, v140
	v_max_f32_e32 v131, v132, v132
	v_and_b32_e32 v134, 0xffff0000, v134
	v_max_f32_e32 v131, 0x358637bd, v131
	v_mov_b32_e32 v129, v131
	v_max_f32_e32 v131, v134, v134
	v_lshlrev_b32_e32 v139, 16, v133
	v_max_f32_e32 v131, 0x358637bd, v131
	v_max_f32_e32 v132, v139, v139
	v_lshlrev_b32_e32 v141, 16, v135
	v_max_f32_e32 v132, 0x358637bd, v132
	v_max_f32_e32 v134, 0x358637bd, v141
	v_max_f32_e32 v139, 0x358637bd, v142
	v_rcp_f32_e32 v139, v139
	v_and_b32_e32 v133, 0xffff0000, v133
	v_and_b32_e32 v135, 0xffff0000, v135
	v_max_f32_e32 v133, 0x358637bd, v133
	v_max_f32_e32 v135, 0x358637bd, v135
	v_mov_b32_e32 v138, 1.0
	v_pk_mul_f32 v[6:7], v[6:7], v[132:133]
	v_pk_mul_f32 v[4:5], v[4:5], v[128:129]
	v_pk_mul_f32 v[2:3], v[2:3], v[134:135]
	s_and_b64 vcc, exec, s[4:5]
	v_pk_mul_f32 v[0:1], v[0:1], v[130:131]
	v_cvt_pk_bf16_f32 v128, v4, v5
	v_cvt_pk_bf16_f32 v129, v6, v7
	v_cvt_pk_bf16_f32 v130, v0, v1
	v_cvt_pk_bf16_f32 v131, v2, v3
	global_store_dwordx4 v[136:137], v[128:131], off offset:256
	s_nop 1
